# layer-0 LayerNorm phases: the 8 loads of each split-K slice issued together for context rows (were waited pair by pair)
# speedup vs baseline: 1.0000x; 1.0000x over previous
; __device__ __forceinline__ void ln_phase(int nrows, const float* src_lat, const float* src_ctx, const float* g, const float* b, float* dst_lat, float* dst_ctx, ...
;     ...
;         if (part && r >= ROWS_LAT) {
;             f32x4 a[8];
; #pragma unroll
;             for (int i = 0; i < 8; ++i) a[i] = pbias ? *(const f32x4*)(pbias + LN_C(i)) : (f32x4){0.f, 0.f, 0.f, 0.f};
; #pragma unroll 1
;             for (int k = 0; k < 8; ++k) { const float* pp = part + ((size_t)k * ROWS_CTX + (r - ROWS_LAT)) * D;
; #pragma unroll
;                 for (int i = 0; i < 8; ++i) a[i] += *(const f32x4*)(pp + LN_C(i)); }
; #pragma unroll
;             for (int i = 0; i < 8; ++i) v[i] = ALPHA * v[i] + *(const f32x4*)(pgate + LN_C(i)) * a[i];
;         }
.LBB0_770:
	v_add_u32_e32 v64, s24, v172
	v_lshlrev_b64 v[114:115], 13, v[64:65]
	v_lshl_add_u64 v[180:181], s[14:15], 0, v[114:115]
	v_mov_b32_e32 v175, v65
	v_lshl_add_u64 v[182:183], v[180:181], 0, v[174:175]
	v_lshlrev_b32_e32 v64, 2, v120
	v_lshl_add_u64 v[176:177], v[180:181], 0, v[64:65]
	v_lshlrev_b32_e32 v64, 2, v122
	v_lshl_add_u64 v[178:179], v[180:181], 0, v[64:65]
	global_load_dwordx4 v[204:207], v[182:183], off offset:16
	global_load_dwordx4 v[208:211], v[182:183], off
	global_load_dwordx4 v[212:215], v[182:183], off offset:2064
	global_load_dwordx4 v[216:219], v[182:183], off offset:2048
	global_load_dwordx4 v[220:223], v[176:177], off offset:16
	global_load_dwordx4 v[224:227], v[176:177], off
	global_load_dwordx4 v[228:231], v[178:179], off offset:16
	global_load_dwordx4 v[232:235], v[178:179], off
	s_addk_i32 s24, 0x400
	s_cmpk_lg_i32 s24, 0xe000
	s_waitcnt vmcnt(7)
	v_pk_add_f32 v[56:57], v[56:57], v[204:205]
	v_pk_add_f32 v[58:59], v[58:59], v[206:207]
	s_waitcnt vmcnt(6)
	v_pk_add_f32 v[60:61], v[60:61], v[208:209]
	v_pk_add_f32 v[62:63], v[62:63], v[210:211]
	s_waitcnt vmcnt(5)
	v_pk_add_f32 v[48:49], v[48:49], v[212:213]
	v_pk_add_f32 v[50:51], v[50:51], v[214:215]
	s_waitcnt vmcnt(4)
	v_pk_add_f32 v[52:53], v[52:53], v[216:217]
	v_pk_add_f32 v[54:55], v[54:55], v[218:219]
	s_waitcnt vmcnt(3)
	v_pk_add_f32 v[40:41], v[40:41], v[220:221]
	v_pk_add_f32 v[42:43], v[42:43], v[222:223]
	s_waitcnt vmcnt(2)
	v_pk_add_f32 v[44:45], v[44:45], v[224:225]
	v_pk_add_f32 v[46:47], v[46:47], v[226:227]
	s_waitcnt vmcnt(1)
	v_pk_add_f32 v[32:33], v[32:33], v[228:229]
	v_pk_add_f32 v[34:35], v[34:35], v[230:231]
	s_waitcnt vmcnt(0)
	v_pk_add_f32 v[36:37], v[36:37], v[232:233]
	v_pk_add_f32 v[38:39], v[38:39], v[234:235]
	s_cbranch_scc1 .LBB0_770
	global_load_dwordx4 v[114:117], v[124:125], off offset:16
	global_load_dwordx4 v[176:179], v[124:125], off
	s_waitcnt vmcnt(1)
	v_pk_mul_f32 v[58:59], v[58:59], v[116:117]
	s_waitcnt vmcnt(0)
	v_pk_mul_f32 v[62:63], v[62:63], v[178:179]
	v_pk_mul_f32 v[60:61], v[60:61], v[176:177]
	v_pk_mul_f32 v[56:57], v[56:57], v[114:115]
	v_pk_fma_f32 v[2:3], v[2:3], s[94:95], v[62:63] op_sel_hi:[1,0,1]
	v_pk_fma_f32 v[0:1], v[0:1], s[94:95], v[60:61] op_sel_hi:[1,0,1]
	v_pk_fma_f32 v[4:5], v[4:5], s[94:95], v[56:57] op_sel_hi:[1,0,1]
	v_pk_fma_f32 v[6:7], v[6:7], s[94:95], v[58:59] op_sel_hi:[1,0,1]
	global_load_dwordx4 v[56:59], v[148:149], off offset:16
	global_load_dwordx4 v[60:63], v[148:149], off
	s_waitcnt vmcnt(1)
	v_pk_mul_f32 v[50:51], v[50:51], v[58:59]
	s_waitcnt vmcnt(0)
	v_pk_mul_f32 v[54:55], v[54:55], v[62:63]
	v_pk_mul_f32 v[52:53], v[52:53], v[60:61]
	v_pk_mul_f32 v[48:49], v[48:49], v[56:57]
	v_pk_fma_f32 v[8:9], v[8:9], s[94:95], v[52:53] op_sel_hi:[1,0,1]
	v_pk_fma_f32 v[10:11], v[10:11], s[94:95], v[54:55] op_sel_hi:[1,0,1]
	v_pk_fma_f32 v[12:13], v[12:13], s[94:95], v[48:49] op_sel_hi:[1,0,1]
	v_pk_fma_f32 v[14:15], v[14:15], s[94:95], v[50:51] op_sel_hi:[1,0,1]
	global_load_dwordx4 v[48:51], v[150:151], off offset:16
	global_load_dwordx4 v[52:55], v[150:151], off
	s_waitcnt vmcnt(1)
	v_pk_mul_f32 v[42:43], v[42:43], v[50:51]
	s_waitcnt vmcnt(0)
	v_pk_mul_f32 v[46:47], v[46:47], v[54:55]
	v_pk_mul_f32 v[44:45], v[44:45], v[52:53]
	v_pk_mul_f32 v[40:41], v[40:41], v[48:49]
	v_pk_fma_f32 v[16:17], v[16:17], s[94:95], v[44:45] op_sel_hi:[1,0,1]
	v_pk_fma_f32 v[18:19], v[18:19], s[94:95], v[46:47] op_sel_hi:[1,0,1]
	v_pk_fma_f32 v[20:21], v[20:21], s[94:95], v[40:41] op_sel_hi:[1,0,1]
	v_pk_fma_f32 v[22:23], v[22:23], s[94:95], v[42:43] op_sel_hi:[1,0,1]
	global_load_dwordx4 v[40:43], v[152:153], off offset:16
	global_load_dwordx4 v[44:47], v[152:153], off
	s_waitcnt vmcnt(1)
	v_pk_mul_f32 v[34:35], v[34:35], v[42:43]
	s_waitcnt vmcnt(0)
	v_pk_mul_f32 v[38:39], v[38:39], v[46:47]
	v_pk_mul_f32 v[36:37], v[36:37], v[44:45]
	v_pk_mul_f32 v[32:33], v[32:33], v[40:41]
	v_pk_fma_f32 v[30:31], v[30:31], s[94:95], v[34:35] op_sel_hi:[1,0,1]
	v_pk_fma_f32 v[24:25], v[24:25], s[94:95], v[36:37] op_sel_hi:[1,0,1]
	v_pk_fma_f32 v[26:27], v[26:27], s[94:95], v[38:39] op_sel_hi:[1,0,1]
	v_pk_fma_f32 v[28:29], v[28:29], s[94:95], v[32:33] op_sel_hi:[1,0,1]
	s_nop 0
	v_mov_b64_e32 v[62:63], v[30:31]
	v_mov_b64_e32 v[60:61], v[28:29]
	v_mov_b64_e32 v[58:59], v[26:27]
	v_mov_b64_e32 v[56:57], v[24:25]
	v_mov_b64_e32 v[54:55], v[22:23]
	v_mov_b64_e32 v[52:53], v[20:21]
	v_mov_b64_e32 v[50:51], v[18:19]
	v_mov_b64_e32 v[48:49], v[16:17]
	v_mov_b64_e32 v[46:47], v[14:15]
	v_mov_b64_e32 v[44:45], v[12:13]
	v_mov_b64_e32 v[42:43], v[10:11]
	v_mov_b64_e32 v[40:41], v[8:9]
	v_mov_b64_e32 v[38:39], v[6:7]
	v_mov_b64_e32 v[36:37], v[4:5]
	v_mov_b64_e32 v[34:35], v[2:3]
	v_mov_b64_e32 v[32:33], v[0:1]

; __device__ __forceinline__ void ln_phase(int nrows, const float* src_lat, const float* src_ctx, const float* g, const float* b, float* dst_lat, float* dst_ctx, ...
;     ...
;         if (part && r >= ROWS_LAT) {
;             f32x4 a[8];
; #pragma unroll
;             for (int i = 0; i < 8; ++i) a[i] = pbias ? *(const f32x4*)(pbias + LN_C(i)) : (f32x4){0.f, 0.f, 0.f, 0.f};
; #pragma unroll 1
;             for (int k = 0; k < 8; ++k) { const float* pp = part + ((size_t)k * ROWS_CTX + (r - ROWS_LAT)) * D;
; #pragma unroll
;                 for (int i = 0; i < 8; ++i) a[i] += *(const f32x4*)(pp + LN_C(i)); }
; #pragma unroll
;             for (int i = 0; i < 8; ++i) v[i] = ALPHA * v[i] + *(const f32x4*)(pgate + LN_C(i)) * a[i];
;         }
.LBB0_1073:
	v_add_u32_e32 v64, s12, v182
	v_lshlrev_b64 v[66:67], 13, v[64:65]
	v_lshl_add_u64 v[66:67], s[24:25], 0, v[66:67]
	v_mov_b32_e32 v185, v65
	v_lshl_add_u64 v[190:191], v[66:67], 0, v[184:185]
	v_lshlrev_b32_e32 v64, 2, v132
	v_lshl_add_u64 v[186:187], v[66:67], 0, v[64:65]
	v_lshlrev_b32_e32 v64, 2, v134
	v_lshl_add_u64 v[66:67], v[66:67], 0, v[64:65]
	global_load_dwordx4 v[206:209], v[190:191], off offset:16
	global_load_dwordx4 v[210:213], v[190:191], off
	global_load_dwordx4 v[214:217], v[190:191], off offset:2064
	global_load_dwordx4 v[218:221], v[190:191], off offset:2048
	global_load_dwordx4 v[222:225], v[186:187], off offset:16
	global_load_dwordx4 v[226:229], v[186:187], off
	global_load_dwordx4 v[230:233], v[66:67], off offset:16
	global_load_dwordx4 v[234:237], v[66:67], off
	s_addk_i32 s12, 0x400
	s_cmpk_lg_i32 s12, 0xe000
	s_waitcnt vmcnt(7)
	v_pk_add_f32 v[60:61], v[60:61], v[206:207]
	v_pk_add_f32 v[62:63], v[62:63], v[208:209]
	s_waitcnt vmcnt(6)
	v_pk_add_f32 v[56:57], v[56:57], v[210:211]
	v_pk_add_f32 v[58:59], v[58:59], v[212:213]
	s_waitcnt vmcnt(5)
	v_pk_add_f32 v[52:53], v[52:53], v[214:215]
	v_pk_add_f32 v[54:55], v[54:55], v[216:217]
	s_waitcnt vmcnt(4)
	v_pk_add_f32 v[48:49], v[48:49], v[218:219]
	v_pk_add_f32 v[50:51], v[50:51], v[220:221]
	s_waitcnt vmcnt(3)
	v_pk_add_f32 v[44:45], v[44:45], v[222:223]
	v_pk_add_f32 v[46:47], v[46:47], v[224:225]
	s_waitcnt vmcnt(2)
	v_pk_add_f32 v[40:41], v[40:41], v[226:227]
	v_pk_add_f32 v[42:43], v[42:43], v[228:229]
	s_waitcnt vmcnt(1)
	v_pk_add_f32 v[32:33], v[32:33], v[230:231]
	v_pk_add_f32 v[34:35], v[34:35], v[232:233]
	s_waitcnt vmcnt(0)
	v_pk_add_f32 v[36:37], v[36:37], v[234:235]
	v_pk_add_f32 v[38:39], v[38:39], v[236:237]
	s_cbranch_scc1 .LBB0_1073
	global_load_dwordx4 v[116:119], v[136:137], off offset:16
	global_load_dwordx4 v[186:189], v[136:137], off
	s_waitcnt vmcnt(0)
	v_pk_mul_f32 v[58:59], v[58:59], v[188:189]
	v_pk_mul_f32 v[56:57], v[56:57], v[186:187]
	v_pk_fma_f32 v[2:3], v[2:3], s[94:95], v[58:59] op_sel_hi:[1,0,1]
	v_pk_fma_f32 v[0:1], v[0:1], s[94:95], v[56:57] op_sel_hi:[1,0,1]
	v_pk_mul_f32 v[56:57], v[62:63], v[118:119]
	v_pk_mul_f32 v[58:59], v[60:61], v[116:117]
	v_pk_fma_f32 v[6:7], v[6:7], s[94:95], v[56:57] op_sel_hi:[1,0,1]
	v_pk_fma_f32 v[4:5], v[4:5], s[94:95], v[58:59] op_sel_hi:[1,0,1]
	global_load_dwordx4 v[56:59], v[160:161], off offset:16
	global_load_dwordx4 v[60:63], v[160:161], off
	s_waitcnt vmcnt(0)
	v_pk_mul_f32 v[50:51], v[50:51], v[62:63]
	v_pk_mul_f32 v[48:49], v[48:49], v[60:61]
	v_pk_fma_f32 v[10:11], v[10:11], s[94:95], v[50:51] op_sel_hi:[1,0,1]
	v_pk_fma_f32 v[8:9], v[8:9], s[94:95], v[48:49] op_sel_hi:[1,0,1]
	v_pk_mul_f32 v[48:49], v[54:55], v[58:59]
	v_pk_mul_f32 v[50:51], v[52:53], v[56:57]
	v_pk_fma_f32 v[14:15], v[14:15], s[94:95], v[48:49] op_sel_hi:[1,0,1]
	v_pk_fma_f32 v[12:13], v[12:13], s[94:95], v[50:51] op_sel_hi:[1,0,1]
	global_load_dwordx4 v[48:51], v[170:171], off offset:16
	global_load_dwordx4 v[52:55], v[170:171], off
	s_waitcnt vmcnt(0)
	v_pk_mul_f32 v[42:43], v[42:43], v[54:55]
	v_pk_mul_f32 v[40:41], v[40:41], v[52:53]
	v_pk_fma_f32 v[18:19], v[18:19], s[94:95], v[42:43] op_sel_hi:[1,0,1]
	v_pk_fma_f32 v[16:17], v[16:17], s[94:95], v[40:41] op_sel_hi:[1,0,1]
	v_pk_mul_f32 v[40:41], v[46:47], v[50:51]
	v_pk_mul_f32 v[42:43], v[44:45], v[48:49]
	v_pk_fma_f32 v[22:23], v[22:23], s[94:95], v[40:41] op_sel_hi:[1,0,1]
	v_pk_fma_f32 v[20:21], v[20:21], s[94:95], v[42:43] op_sel_hi:[1,0,1]
	global_load_dwordx4 v[40:43], v[172:173], off offset:16
	global_load_dwordx4 v[44:47], v[172:173], off
	s_waitcnt vmcnt(1)
	v_pk_mul_f32 v[34:35], v[34:35], v[42:43]
	s_waitcnt vmcnt(0)
	v_pk_mul_f32 v[38:39], v[38:39], v[46:47]
	v_pk_mul_f32 v[36:37], v[36:37], v[44:45]
	v_pk_mul_f32 v[32:33], v[32:33], v[40:41]
	v_pk_fma_f32 v[30:31], v[30:31], s[94:95], v[34:35] op_sel_hi:[1,0,1]
	v_pk_fma_f32 v[24:25], v[24:25], s[94:95], v[36:37] op_sel_hi:[1,0,1]
	v_pk_fma_f32 v[26:27], v[26:27], s[94:95], v[38:39] op_sel_hi:[1,0,1]
	v_pk_fma_f32 v[28:29], v[28:29], s[94:95], v[32:33] op_sel_hi:[1,0,1]
	s_nop 0
	v_mov_b64_e32 v[62:63], v[30:31]
	v_mov_b64_e32 v[60:61], v[28:29]
	v_mov_b64_e32 v[58:59], v[26:27]
	v_mov_b64_e32 v[56:57], v[24:25]
	v_mov_b64_e32 v[54:55], v[22:23]
	v_mov_b64_e32 v[52:53], v[20:21]
	v_mov_b64_e32 v[50:51], v[18:19]
	v_mov_b64_e32 v[48:49], v[16:17]
	v_mov_b64_e32 v[46:47], v[14:15]
	v_mov_b64_e32 v[44:45], v[12:13]
	v_mov_b64_e32 v[42:43], v[10:11]
	v_mov_b64_e32 v[40:41], v[8:9]
	v_mov_b64_e32 v[38:39], v[6:7]
	v_mov_b64_e32 v[36:37], v[4:5]
	v_mov_b64_e32 v[34:35], v[2:3]
	v_mov_b64_e32 v[32:33], v[0:1]
